# attention: wave halves staggered by half a tile (waves 0-3 barrier after PV, waves 4-7 barrier between QK and PV), 4-deep V ring
# speedup vs baseline: 1.0025x; 1.0025x over previous
.LBB0_725:
	s_ashr_i32 s42, s4, 8
	s_ashr_i32 s43, s42, 31
	s_lshl_b32 s10, s4, 8
	s_lshl_b64 s[46:47], s[42:43], 13
	s_and_b32 s10, s10, 0x1f00
	s_or_b32 s46, s46, s10
	s_lshl_b32 s2, s4, 1
	s_mul_i32 s10, s47, 0xc00
	s_mul_hi_u32 s11, s46, 0xc00
	s_and_b32 s2, s2, 0x100
	s_bfe_u32 s3, s4, 0x30005
	s_add_i32 s11, s11, s10
	s_mul_i32 s10, s46, 0xc00
	s_add_u32 s16, s6, s10
	s_addc_u32 s11, s7, s11
	s_lshl_b32 s10, s3, 7
	s_lshl_b32 s3, s3, 8
	s_add_u32 s18, s16, s3
	s_addc_u32 s19, s11, 0
	s_mul_i32 s11, s42, 0x1800000
	s_mul_hi_i32 s3, s42, 0x1800000
	s_add_u32 s11, s6, s11
	s_addc_u32 s3, s7, s3
	s_and_b32 s16, s4, 0x80
	s_lshl_b32 s16, s16, 1
	s_add_u32 s40, s11, s16
	v_mov_b32_e32 v48, v192
	s_addc_u32 s41, s3, 0
	s_barrier
	s_add_i32 s3, 0, 0x10000
	v_and_b32_e32 v0, 0x3fffffc0, v48
	v_lshl_add_u32 v177, v0, 2, s3
	v_ashrrev_i32_e32 v0, 1, v48
	s_movk_i32 s3, 0xffe0
	v_bfe_u32 v181, v48, 5, 1
	v_and_b32_e32 v176, 0xffffffe0, v0
	v_bfi_b32 v2, s3, v0, v48
	v_mov_b64_e32 v[0:1], s[18:19]
	s_movk_i32 s20, 0xc00
	v_mad_i64_i32 v[0:1], s[18:19], v2, s20, v[0:1]
	v_lshlrev_b32_e32 v194, 4, v181
	v_lshl_add_u64 v[0:1], v[0:1], 0, v[194:195]
	v_ashrrev_i32_e32 v50, 4, v48
	global_load_dwordx4 v[124:127], v[0:1], off
	global_load_dwordx4 v[120:123], v[0:1], off offset:32
	global_load_dwordx4 v[116:119], v[0:1], off offset:64
	global_load_dwordx4 v[112:115], v[0:1], off offset:96
	global_load_dwordx4 v[108:111], v[0:1], off offset:128
	global_load_dwordx4 v[104:107], v[0:1], off offset:160
	global_load_dwordx4 v[100:103], v[0:1], off offset:192
	global_load_dwordx4 v[96:99], v[0:1], off offset:224
	v_and_b32_e32 v1, 0xfffff0, v50
	v_lshlrev_b32_e32 v2, 1, v50
	v_lshlrev_b32_e32 v0, 3, v48
	v_and_or_b32 v1, v2, 8, v1
	v_and_b32_e32 v52, 0x78, v0
	v_lshrrev_b32_e32 v2, 1, v50
	v_lshrrev_b32_e32 v1, 1, v1
	v_bfe_u32 v0, v0, 5, 2
	v_and_b32_e32 v3, 3, v50
	v_or_b32_e32 v1, v1, v0
	v_and_or_b32 v2, v2, 4, v3
	v_lshlrev_b32_e32 v16, 1, v52
	v_lshlrev_b32_e32 v1, 9, v1
	v_lshlrev_b32_e32 v2, 6, v2
	v_and_b32_e32 v3, 48, v16
	v_add_u32_e32 v18, 32, v50
	v_or3_b32 v17, v1, v2, v3
	v_and_b32_e32 v1, 0xfffff0, v18
	v_lshlrev_b32_e32 v4, 1, v18
	v_and_or_b32 v1, v4, 8, v1
	v_lshrrev_b32_e32 v1, 1, v1
	v_or_b32_e32 v0, v1, v0
	v_and_b32_e32 v49, 63, v48
	v_lshlrev_b32_e32 v0, 9, v0
	v_lshlrev_b32_e32 v20, 4, v48
	v_or3_b32 v19, v0, v2, v3
	v_lshlrev_b32_e32 v0, 3, v49
	v_and_b32_e32 v1, 0xc0, v20
	v_lshlrev_b32_e32 v2, 1, v48
	v_and_or_b32 v1, v0, 24, v1
	v_and_b32_e32 v2, 32, v2
	v_and_b32_e32 v0, 0x100, v0
	s_movk_i32 s16, 0x600
	v_or3_b32 v51, v1, v2, v0
	v_mad_i64_i32 v[0:1], s[18:19], v50, s16, 0
	v_or_b32_e32 v0, v0, v52
	v_lshl_add_u64 v[8:9], v[0:1], 1, s[40:41]
	global_load_dwordx4 v[0:3], v[8:9], off offset:2560
	v_mad_i64_i32 v[4:5], s[18:19], v18, s16, 0
	v_or_b32_e32 v4, v4, v52
	v_lshl_add_u64 v[12:13], v[4:5], 1, s[40:41]
	global_load_dwordx4 v[4:7], v[12:13], off offset:2560
	s_nop 0
	global_load_dwordx4 v[8:11], v[8:9], off offset:2048
	s_nop 0
	global_load_dwordx4 v[12:15], v[12:13], off offset:2048
	v_add_u32_e32 v183, 0, v17
	s_waitcnt vmcnt(0)
	v_and_b32_e32 v180, 31, v48
	v_lshlrev_b32_e32 v53, 8, v180
	v_and_b32_e32 v62, 0x70, v20
	v_add_u32_e32 v184, 0, v19
	v_or_b32_e32 v54, 32, v194
	v_bitop3_b32 v54, v54, v53, v62 bitop3:0xde
	v_add_u32_e32 v205, 0, v54
	s_cmp_lg_u32 0, -1
	s_cselect_b32 s3, 0, 0
	s_mov_b32 s53, s52
	s_mov_b32 s54, s52
	s_mov_b32 s55, s52
	s_mov_b32 s56, s52
	s_mov_b32 s57, s52
	s_mov_b32 s58, s52
	s_mov_b32 s59, s52
	s_mov_b32 s60, s52
	s_mov_b32 s61, s52
	s_mov_b32 s62, s52
	s_mov_b32 s63, s52
	s_mov_b32 s64, s52
	s_mov_b32 s65, s52
	s_mov_b32 s66, s52
	s_mov_b32 s67, s52
	v_add_u32_e32 v182, s3, v51
	s_mov_b32 s11, -1
	v_lshl_add_u32 v185, v180, 2, v177
	s_movk_i32 s15, 0xc00
	v_mov_b32_e32 v186, 0
	s_waitcnt vmcnt(3)
	ds_write_b128 v183, v[0:3]
	v_lshlrev_b32_e32 v0, 8, v50
	v_and_b32_e32 v1, 0x70, v48
	v_bitop3_b32 v0, v16, v0, v1 bitop3:0xde
	v_add_u32_e32 v188, 0, v0
	v_lshlrev_b32_e32 v0, 8, v18
	v_bitop3_b32 v0, v16, v0, v1 bitop3:0xde
	v_add_u32_e32 v189, 0, v0
	v_bitop3_b32 v0, v194, v53, v62 bitop3:0xde
	v_add_u32_e32 v190, 0, v0
	s_waitcnt vmcnt(2)
	ds_write_b128 v184, v[4:7]
	s_waitcnt vmcnt(1)
	ds_write_b128 v188, v[8:11] offset:32768
	s_waitcnt vmcnt(0)
	ds_write_b128 v189, v[12:15] offset:32768
	s_waitcnt lgkmcnt(0)
	s_barrier
	ds_read_b128 v[16:19], v190 offset:32768
	ds_read_b128 v[20:23], v190 offset:40960
	s_waitcnt lgkmcnt(1)
	v_mfma_f32_32x32x16_bf16 v[32:47], v[16:19], v[124:127], 0
	ds_read_b128 v[54:57], v205 offset:32768
	ds_read_b128 v[58:61], v205 offset:40960
	v_mov_b64_e32 v[0:1], s[52:53]
	v_mov_b64_e32 v[14:15], s[66:67]
	v_mov_b64_e32 v[2:3], s[54:55]
	v_mov_b64_e32 v[4:5], s[56:57]
	v_mov_b64_e32 v[6:7], s[58:59]
	v_mov_b64_e32 v[8:9], s[60:61]
	s_waitcnt lgkmcnt(2)
	v_mfma_f32_32x32x16_bf16 v[16:31], v[20:23], v[124:127], 0
	v_mov_b64_e32 v[10:11], s[62:63]
	v_mov_b64_e32 v[12:13], s[64:65]
	s_waitcnt lgkmcnt(1)
	v_mfma_f32_32x32x16_bf16 v[32:47], v[54:57], v[120:123], v[32:47]
	v_or_b32_e32 v54, 64, v194
	v_bitop3_b32 v54, v54, v53, v62 bitop3:0xde
	v_add_u32_e32 v204, 0, v54
	s_waitcnt lgkmcnt(0)
	v_mfma_f32_32x32x16_bf16 v[16:31], v[58:61], v[120:123], v[16:31]
	ds_read_b128 v[54:57], v204 offset:32768
	ds_read_b128 v[58:61], v204 offset:40960
	s_waitcnt lgkmcnt(1)
	v_mfma_f32_32x32x16_bf16 v[32:47], v[54:57], v[116:119], v[32:47]
	v_or_b32_e32 v54, 0x60, v194
	v_bitop3_b32 v54, v54, v53, v62 bitop3:0xde
	v_add_u32_e32 v202, 0, v54
	s_waitcnt lgkmcnt(0)
	v_mfma_f32_32x32x16_bf16 v[16:31], v[58:61], v[116:119], v[16:31]
	ds_read_b128 v[54:57], v202 offset:32768
	ds_read_b128 v[58:61], v202 offset:40960
	s_waitcnt lgkmcnt(1)
	v_mfma_f32_32x32x16_bf16 v[32:47], v[54:57], v[112:115], v[32:47]
	v_or_b32_e32 v54, 0x80, v194
	v_bitop3_b32 v54, v54, v53, v62 bitop3:0xde
	v_add_u32_e32 v191, 0, v54
	s_waitcnt lgkmcnt(0)
	v_mfma_f32_32x32x16_bf16 v[16:31], v[58:61], v[112:115], v[16:31]
	ds_read_b128 v[54:57], v191 offset:32768
	ds_read_b128 v[58:61], v191 offset:40960
	s_waitcnt lgkmcnt(1)
	v_mfma_f32_32x32x16_bf16 v[32:47], v[54:57], v[108:111], v[32:47]
	v_or_b32_e32 v54, 0xa0, v194
	v_bitop3_b32 v54, v54, v53, v62 bitop3:0xde
	v_add_u32_e32 v203, 0, v54
	s_waitcnt lgkmcnt(0)
	v_mfma_f32_32x32x16_bf16 v[16:31], v[58:61], v[108:111], v[16:31]
	ds_read_b128 v[54:57], v203 offset:32768
	ds_read_b128 v[58:61], v203 offset:40960
	s_waitcnt lgkmcnt(1)
	v_mfma_f32_32x32x16_bf16 v[32:47], v[54:57], v[104:107], v[32:47]
	v_or_b32_e32 v54, 0xc0, v194
	v_bitop3_b32 v54, v54, v53, v62 bitop3:0xde
	v_add_u32_e32 v206, 0, v54
	s_waitcnt lgkmcnt(0)
	v_mfma_f32_32x32x16_bf16 v[16:31], v[58:61], v[104:107], v[16:31]
	ds_read_b128 v[54:57], v206 offset:32768
	ds_read_b128 v[58:61], v206 offset:40960
	s_waitcnt lgkmcnt(1)
	v_mfma_f32_32x32x16_bf16 v[32:47], v[54:57], v[100:103], v[32:47]
	v_or_b32_e32 v54, 0xe0, v194
	v_bitop3_b32 v53, v54, v53, v62 bitop3:0xde
	v_add_u32_e32 v207, 0, v53
	s_waitcnt lgkmcnt(0)
	v_mfma_f32_32x32x16_bf16 v[16:31], v[58:61], v[100:103], v[16:31]
	ds_read_b128 v[54:57], v207 offset:32768
	ds_read_b128 v[58:61], v207 offset:40960
	s_waitcnt lgkmcnt(1)
	v_mfma_f32_32x32x16_bf16 v[32:47], v[54:57], v[96:99], v[32:47]
	v_mov_b32_e32 v55, 0xf149f2ca
	s_waitcnt lgkmcnt(0)
	v_mfma_f32_32x32x16_bf16 v[16:31], v[58:61], v[96:99], v[16:31]
	s_nop 8
	v_max_f32_e32 v53, v33, v33
	v_max_f32_e32 v54, v32, v32
	v_max_f32_e32 v53, v54, v53
	v_max3_f32 v53, v53, v34, v35
	v_max3_f32 v53, v53, v36, v37
	v_max3_f32 v53, v53, v38, v39
	v_max3_f32 v53, v53, v40, v41
	v_max3_f32 v53, v53, v42, v43
	v_max3_f32 v53, v53, v44, v45
	v_max3_f32 v53, v53, v46, v47
	v_max3_f32 v53, v53, v16, v17
	v_max3_f32 v53, v53, v18, v19
	v_max3_f32 v53, v53, v20, v21
	v_max3_f32 v53, v53, v22, v23
	v_max3_f32 v53, v53, v24, v25
	v_max3_f32 v53, v53, v26, v27
	v_max3_f32 v53, v53, v28, v29
	v_max3_f32 v53, v53, v30, v31
	v_mov_b32_e32 v54, v53
	s_nop 1
	v_permlane32_swap_b32_e32 v53, v54
	v_max_f32_e32 v54, v54, v54
	v_max_f32_e32 v53, v53, v53
	v_max_f32_e32 v53, v53, v54
	v_add_f32_e32 v54, 0x7149f2ca, v53
	v_max_f32_e32 v53, 0xf149f2ca, v53
	v_cmp_ge_f32_e32 vcc, s85, v54
	v_sub_f32_e32 v54, 0xf149f2ca, v53
	v_mul_f32_e32 v54, 0x3e0293ee, v54
	v_exp_f32_e32 v54, v54
	s_cmp_eq_u64 vcc, exec
	s_cselect_b64 vcc, -1, 0
	v_cndmask_b32_e32 v164, v53, v55, vcc
	v_cndmask_b32_e64 v208, v54, 1.0, vcc
	v_mul_f32_e32 v54, 0xbe0293ee, v164
	v_pk_fma_f32 v[148:149], v[20:21], s[12:13], v[54:55] op_sel_hi:[1,0,0]
	v_pk_fma_f32 v[156:157], v[16:17], s[12:13], v[54:55] op_sel_hi:[1,0,0]
	v_add_u32_e32 v16, 64, v50
	v_add_u32_e32 v20, 0x60, v50
	v_mad_i64_i32 v[16:17], s[18:19], v16, s16, 0
	v_mad_i64_i32 v[20:21], s[18:19], v20, s16, 0
	v_or_b32_e32 v16, v16, v52
	v_or_b32_e32 v20, v20, v52
	v_pk_fma_f32 v[152:153], v[28:29], s[12:13], v[54:55] op_sel_hi:[1,0,0]
	v_pk_fma_f32 v[144:145], v[24:25], s[12:13], v[54:55] op_sel_hi:[1,0,0]
	v_lshl_add_u64 v[24:25], v[16:17], 1, s[40:41]
	v_lshl_add_u64 v[28:29], v[20:21], 1, s[40:41]
	v_fmamk_f32 v32, v32, 0x3e0293ee, v54
	v_fmamk_f32 v34, v34, 0x3e0293ee, v54
	v_pk_fma_f32 v[150:151], v[30:31], s[12:13], v[54:55] op_sel_hi:[1,0,0]
	v_pk_fma_f32 v[158:159], v[26:27], s[12:13], v[54:55] op_sel_hi:[1,0,0]
	v_pk_fma_f32 v[146:147], v[22:23], s[12:13], v[54:55] op_sel_hi:[1,0,0]
	v_pk_fma_f32 v[154:155], v[18:19], s[12:13], v[54:55] op_sel_hi:[1,0,0]
	global_load_dwordx4 v[16:19], v[24:25], off offset:2560
	global_load_dwordx4 v[20:23], v[28:29], off offset:2560
	s_nop 0
	global_load_dwordx4 v[24:27], v[24:25], off offset:2048
	s_nop 0
	global_load_dwordx4 v[28:31], v[28:29], off offset:2048
	v_fmamk_f32 v33, v33, 0x3e0293ee, v54
	v_fmamk_f32 v35, v35, 0x3e0293ee, v54
	v_exp_f32_e32 v238, v32
	v_exp_f32_e32 v240, v34
	v_add_u32_e32 v32, 0x80, v50
	v_add_u32_e32 v34, 0xa0, v50
	v_exp_f32_e32 v239, v33
	v_exp_f32_e32 v246, v35
	v_mad_i64_i32 v[32:33], s[18:19], v32, s16, 0
	v_mad_i64_i32 v[34:35], s[18:19], v34, s16, 0
	v_or_b32_e32 v32, v32, v52
	v_or_b32_e32 v34, v34, v52
	v_lshl_add_u64 v[32:33], v[32:33], 1, s[40:41]
	v_lshl_add_u64 v[34:35], v[34:35], 1, s[40:41]
	global_load_dwordx4 v[128:131], v[32:33], off offset:2560
	global_load_dwordx4 v[132:135], v[34:35], off offset:2560
	global_load_dwordx4 v[136:139], v[32:33], off offset:2048
	global_load_dwordx4 v[140:143], v[34:35], off offset:2048
	v_mov_b32_e32 v53, v54
	s_waitcnt vmcnt(4)
	s_waitcnt vmcnt(7)
	ds_write_b128 v183, v[16:19] offset:16384
	s_waitcnt vmcnt(6)
	ds_write_b128 v184, v[20:23] offset:16384
	s_waitcnt vmcnt(5)
	ds_write_b128 v188, v[24:27] offset:49152
	s_waitcnt vmcnt(4)
	ds_write_b128 v189, v[28:31] offset:49152
	v_mad_i64_i32 v[16:17], s[18:19], v50, s20, 0
	v_mov_b32_e32 v18, 0x1800000
	v_fmamk_f32 v36, v36, 0x3e0293ee, v54
	v_fmamk_f32 v37, v37, 0x3e0293ee, v54
	v_fmamk_f32 v38, v38, 0x3e0293ee, v54
	v_fmamk_f32 v39, v39, 0x3e0293ee, v54
	v_fmamk_f32 v40, v40, 0x3e0293ee, v54
	v_fmamk_f32 v41, v41, 0x3e0293ee, v54
	v_fmamk_f32 v42, v42, 0x3e0293ee, v54
	v_fmamk_f32 v43, v43, 0x3e0293ee, v54
	v_fmamk_f32 v44, v44, 0x3e0293ee, v54
	v_fmamk_f32 v45, v45, 0x3e0293ee, v54
	v_fmamk_f32 v46, v46, 0x3e0293ee, v54
	v_fmac_f32_e32 v53, 0x3e0293ee, v47
	v_mad_i64_i32 v[16:17], s[18:19], s42, v18, v[16:17]
	v_and_b32_e32 v18, 15, v48
	v_exp_f32_e32 v247, v36
	v_exp_f32_e32 v248, v37
	v_exp_f32_e32 v249, v38
	v_exp_f32_e32 v250, v39
	v_exp_f32_e32 v251, v40
	v_exp_f32_e32 v252, v41
	v_exp_f32_e32 v253, v42
	v_exp_f32_e32 v241, v43
	v_exp_f32_e32 v243, v44
	v_exp_f32_e32 v244, v45
	v_exp_f32_e32 v245, v46
	v_exp_f32_e32 v193, v53
	v_lshlrev_b32_e32 v18, 4, v18
	s_addk_i32 s3, 0x4000
	v_or3_b32 v16, v16, s2, v18
	v_cmp_gt_u32_e64 s[40:41], 32, v49
	v_add_u32_e32 v187, s3, v51
	v_lshl_add_u64 v[178:179], s[44:45], 0, v[16:17]
	v_mov_b64_e32 v[62:63], v[14:15]
	v_mov_b64_e32 v[46:47], v[14:15]
	v_mov_b64_e32 v[30:31], v[14:15]
	v_mov_b64_e32 v[60:61], v[12:13]
	v_mov_b64_e32 v[58:59], v[10:11]
	v_mov_b64_e32 v[56:57], v[8:9]
	v_mov_b64_e32 v[54:55], v[6:7]
	v_mov_b64_e32 v[52:53], v[4:5]
	v_mov_b64_e32 v[50:51], v[2:3]
	v_mov_b64_e32 v[48:49], v[0:1]
	v_mov_b64_e32 v[44:45], v[12:13]
	v_mov_b64_e32 v[42:43], v[10:11]
	v_mov_b64_e32 v[40:41], v[8:9]
	v_mov_b64_e32 v[38:39], v[6:7]
	v_mov_b64_e32 v[36:37], v[4:5]
	v_mov_b64_e32 v[34:35], v[2:3]
	v_mov_b64_e32 v[32:33], v[0:1]
	v_mov_b64_e32 v[28:29], v[12:13]
	v_mov_b64_e32 v[26:27], v[10:11]
	v_mov_b64_e32 v[24:25], v[8:9]
	v_mov_b64_e32 v[22:23], v[6:7]
	v_mov_b64_e32 v[20:21], v[4:5]
	v_mov_b64_e32 v[18:19], v[2:3]
	v_mov_b64_e32 v[16:17], v[0:1]
	s_waitcnt lgkmcnt(0)
	s_barrier
	s_mov_b32 s90, 0
	s_movk_i32 s91, 0x4000
	s_mov_b32 s92, 0x10800
	s_mov_b32 s99, 0x14800
	v_readfirstlane_b32 s98, v192
	s_nop 3
	s_lshr_b32 s98, s98, 6
	s_cmp_ge_u32 s98, 4
	s_cbranch_scc1 .Lattn_b_entry

.LBB0_730:
	v_fmamk_f32 v215, v69, 0x3e0293ee, v212
	v_fmamk_f32 v214, v76, 0x3e0293ee, v212
	v_fmamk_f32 v222, v64, 0x3e0293ee, v212
	v_fmamk_f32 v223, v65, 0x3e0293ee, v212
	v_fmamk_f32 v224, v66, 0x3e0293ee, v212
	v_fmamk_f32 v225, v67, 0x3e0293ee, v212
	v_fmamk_f32 v226, v68, 0x3e0293ee, v212
	v_fmamk_f32 v216, v70, 0x3e0293ee, v212
	v_fmamk_f32 v217, v71, 0x3e0293ee, v212
	v_fmamk_f32 v218, v72, 0x3e0293ee, v212
	v_fmamk_f32 v219, v73, 0x3e0293ee, v212
	v_fmamk_f32 v220, v74, 0x3e0293ee, v212
	v_fmamk_f32 v221, v75, 0x3e0293ee, v212
	v_fmamk_f32 v227, v77, 0x3e0293ee, v212
	v_fmamk_f32 v228, v78, 0x3e0293ee, v212
	v_fmac_f32_e32 v212, 0x3e0293ee, v79
	s_waitcnt lgkmcnt(0)
	s_barrier
	ds_read_b128 v[64:67], v190 offset:32768
	ds_read_b128 v[68:71], v190 offset:40960
	ds_read_b128 v[230:233], v205 offset:32768
	ds_read_b128 v[234:237], v205 offset:40960
	v_exp_f32_e32 v222, v222
	v_exp_f32_e32 v223, v223
	v_add_f32_e32 v196, v238, v239
	s_waitcnt lgkmcnt(3)
	v_mfma_f32_32x32x16_bf16 v[80:95], v[64:67], v[124:127], 0
	v_exp_f32_e32 v224, v224
	v_exp_f32_e32 v225, v225
	v_add_f32_e32 v196, v240, v196
	v_add_f32_e32 v196, v246, v196
	s_waitcnt lgkmcnt(2)
	v_mfma_f32_32x32x16_bf16 v[64:79], v[68:71], v[124:127], 0
	v_exp_f32_e32 v226, v226
	v_exp_f32_e32 v215, v215
	v_add_f32_e32 v196, v247, v196
	v_add_f32_e32 v196, v248, v196
	s_waitcnt lgkmcnt(1)
	v_mfma_f32_32x32x16_bf16 v[80:95], v[230:233], v[120:123], v[80:95]
	v_exp_f32_e32 v216, v216
	v_exp_f32_e32 v217, v217
	v_add_f32_e32 v196, v249, v196
	v_add_f32_e32 v196, v250, v196
	s_waitcnt lgkmcnt(0)
	v_mfma_f32_32x32x16_bf16 v[64:79], v[234:237], v[120:123], v[64:79]
	ds_read_b128 v[230:233], v204 offset:32768
	ds_read_b128 v[234:237], v204 offset:40960
	v_exp_f32_e32 v218, v218
	v_exp_f32_e32 v219, v219
	v_add_f32_e32 v196, v251, v196
	v_add_f32_e32 v196, v252, v196
	s_waitcnt lgkmcnt(1)
	v_mfma_f32_32x32x16_bf16 v[80:95], v[230:233], v[116:119], v[80:95]
	v_exp_f32_e32 v220, v220
	v_exp_f32_e32 v221, v221
	v_add_f32_e32 v196, v253, v196
	v_add_f32_e32 v196, v241, v196
	s_waitcnt lgkmcnt(0)
	v_mfma_f32_32x32x16_bf16 v[64:79], v[234:237], v[116:119], v[64:79]
	ds_read_b128 v[230:233], v202 offset:32768
	ds_read_b128 v[234:237], v202 offset:40960
	v_exp_f32_e32 v214, v214
	v_exp_f32_e32 v227, v227
	v_add_f32_e32 v196, v243, v196
	v_add_f32_e32 v196, v244, v196
	s_waitcnt lgkmcnt(1)
	v_mfma_f32_32x32x16_bf16 v[80:95], v[230:233], v[112:115], v[80:95]
	v_exp_f32_e32 v228, v228
	v_exp_f32_e32 v212, v212
	v_add_f32_e32 v196, v245, v196
	v_add_f32_e32 v196, v193, v196
	s_waitcnt lgkmcnt(0)
	v_mfma_f32_32x32x16_bf16 v[64:79], v[234:237], v[112:115], v[64:79]
	ds_read_b128 v[230:233], v191 offset:32768
	ds_read_b128 v[234:237], v191 offset:40960
	v_add_f32_e32 v196, v222, v196
	v_add_f32_e32 v196, v223, v196
	v_add_f32_e32 v196, v224, v196
	v_add_f32_e32 v196, v225, v196
	v_cvt_pk_bf16_f32 v160, v238, v239
	v_cvt_pk_bf16_f32 v162, v247, v248
	s_waitcnt lgkmcnt(1)
	v_mfma_f32_32x32x16_bf16 v[80:95], v[230:233], v[108:111], v[80:95]
	v_add_f32_e32 v196, v226, v196
	v_add_f32_e32 v196, v215, v196
	v_add_f32_e32 v196, v216, v196
	v_add_f32_e32 v196, v217, v196
	v_cvt_pk_bf16_f32 v161, v240, v246
	v_cvt_pk_bf16_f32 v163, v249, v250
	s_waitcnt lgkmcnt(0)
	v_mfma_f32_32x32x16_bf16 v[64:79], v[234:237], v[108:111], v[64:79]
	ds_read_b128 v[230:233], v203 offset:32768
	ds_read_b128 v[234:237], v203 offset:40960
	v_add_f32_e32 v196, v218, v196
	v_add_f32_e32 v196, v219, v196
	v_add_f32_e32 v196, v220, v196
	v_add_f32_e32 v196, v221, v196
	v_permlane32_swap_b32_e32 v160, v162
	v_permlane32_swap_b32_e32 v161, v163
	s_waitcnt lgkmcnt(1)
	v_mfma_f32_32x32x16_bf16 v[80:95], v[230:233], v[104:107], v[80:95]
	v_add_f32_e32 v196, v214, v196
	v_add_f32_e32 v196, v227, v196
	v_add_f32_e32 v196, v228, v196
	v_add_f32_e32 v196, v212, v196
	v_cvt_pk_bf16_f32 v164, v251, v252
	v_cvt_pk_bf16_f32 v166, v243, v244
	s_waitcnt lgkmcnt(0)
	v_mfma_f32_32x32x16_bf16 v[64:79], v[234:237], v[104:107], v[64:79]
	ds_read_b128 v[230:233], v206 offset:32768
	ds_read_b128 v[234:237], v206 offset:40960
	s_waitcnt vmcnt(0)
	ds_write_b128 v188, v[148:151] offset:49152
	ds_write_b128 v189, v[152:155] offset:49152
	v_add_u32_e32 v197, s99, v183
	ds_write_b128 v197, v[144:147]
	v_add_u32_e32 v197, s99, v184
	ds_write_b128 v197, v[156:159]
	v_mov_b32_e32 v198, v196
	v_cvt_pk_bf16_f32 v165, v253, v241
	v_cvt_pk_bf16_f32 v167, v245, v193
	v_cvt_pk_bf16_f32 v168, v222, v223
	v_cvt_pk_bf16_f32 v170, v226, v215
	s_waitcnt lgkmcnt(5)
	v_mfma_f32_32x32x16_bf16 v[80:95], v[230:233], v[100:103], v[80:95]
	v_permlane32_swap_b32_e32 v196, v198
	v_permlane32_swap_b32_e32 v164, v166
	v_permlane32_swap_b32_e32 v165, v167
	v_cvt_pk_bf16_f32 v169, v224, v225
	v_cvt_pk_bf16_f32 v171, v216, v217
	s_waitcnt lgkmcnt(4)
	v_mfma_f32_32x32x16_bf16 v[64:79], v[234:237], v[100:103], v[64:79]
	ds_read_b128 v[230:233], v207 offset:32768
	ds_read_b128 v[234:237], v207 offset:40960
	v_permlane32_swap_b32_e32 v168, v170
	v_cvt_pk_bf16_f32 v172, v218, v219
	v_cvt_pk_bf16_f32 v173, v220, v221
	s_waitcnt lgkmcnt(1)
	v_mfma_f32_32x32x16_bf16 v[80:95], v[230:233], v[96:99], v[80:95]
	v_permlane32_swap_b32_e32 v169, v171
	v_cvt_pk_bf16_f32 v174, v214, v227
	v_cvt_pk_bf16_f32 v175, v228, v212
	s_waitcnt lgkmcnt(0)
	v_mfma_f32_32x32x16_bf16 v[64:79], v[234:237], v[96:99], v[64:79]
	v_permlane32_swap_b32_e32 v172, v174
	v_permlane32_swap_b32_e32 v173, v175
	v_add_f32_e32 v209, v209, v210
	v_fmac_f32_e32 v209, v208, v186
	v_add_f32_e32 v186, v196, v198
	v_fmac_f32_e32 v186, v209, v213
	v_add_u32_e32 v187, s91, v182
	s_cmpk_gt_u32 s11, 0x7c
	s_cselect_b64 s[20:21], -1, 0
	s_and_b64 vcc, exec, s[20:21]
	s_cbranch_vccnz .LBB0_732
	v_add_co_u32_e32 v132, vcc, 0xfffe8000, v178
	s_nop 1
	v_addc_co_u32_e32 v133, vcc, -1, v179, vcc
	global_load_dwordx4 v[128:131], v[132:133], off
	global_load_dwordx4 v[136:139], v[132:133], off offset:-512
	s_nop 0
	global_load_dwordx4 v[132:135], v[178:179], off
	global_load_dwordx4 v[140:143], v[178:179], off offset:-512
.LBB0_732:
	ds_read_b64_tr_b16 v[216:217], v187 offset:0
	ds_read_b64_tr_b16 v[218:219], v187 offset:0x800
	ds_read_b64_tr_b16 v[220:221], v187 offset:0x1000
	ds_read_b64_tr_b16 v[222:223], v187 offset:0x1800
	ds_read_b64_tr_b16 v[224:225], v187 offset:0x2000
	ds_read_b64_tr_b16 v[226:227], v187 offset:0x2800
	ds_read_b64_tr_b16 v[228:229], v187 offset:0x3000
	ds_read_b64_tr_b16 v[230:231], v187 offset:0x3800
	v_max_f32_e32 v196, v81, v81
	v_max_f32_e32 v197, v80, v80
	v_max_f32_e32 v196, v197, v196
	v_max3_f32 v196, v196, v82, v83
	v_max3_f32 v196, v196, v84, v85
	v_max3_f32 v196, v196, v86, v87
	v_max3_f32 v196, v196, v88, v89
	s_waitcnt lgkmcnt(0)
	s_nop 0
	v_mfma_f32_32x32x16_bf16 v[0:15], v[160:163], v[216:219], v[0:15]
	ds_read_b64_tr_b16 v[216:217], v187 offset:0x200
	ds_read_b64_tr_b16 v[218:219], v187 offset:0xa00
	v_max3_f32 v196, v196, v90, v91
	v_max3_f32 v196, v196, v92, v93
	v_max3_f32 v196, v196, v94, v95
	v_max3_f32 v196, v196, v64, v65
	v_mfma_f32_32x32x16_bf16 v[0:15], v[164:167], v[220:223], v[0:15]
	ds_read_b64_tr_b16 v[220:221], v187 offset:0x1200
	ds_read_b64_tr_b16 v[222:223], v187 offset:0x1a00
	v_max3_f32 v196, v196, v66, v67
	v_max3_f32 v196, v196, v68, v69
	v_max3_f32 v196, v196, v70, v71
	v_max3_f32 v196, v196, v72, v73
	v_mfma_f32_32x32x16_bf16 v[0:15], v[168:171], v[224:227], v[0:15]
	ds_read_b64_tr_b16 v[224:225], v187 offset:0x2200
	ds_read_b64_tr_b16 v[226:227], v187 offset:0x2a00
	v_max3_f32 v196, v196, v74, v75
	v_max3_f32 v196, v196, v76, v77
	v_max3_f32 v196, v196, v78, v79
	v_mov_b32_e32 v197, v196
	v_mfma_f32_32x32x16_bf16 v[0:15], v[172:175], v[228:231], v[0:15]
	ds_read_b64_tr_b16 v[228:229], v187 offset:0x3200
	ds_read_b64_tr_b16 v[230:231], v187 offset:0x3a00
	v_permlane32_swap_b32_e32 v196, v197
	v_max_f32_e32 v197, v197, v197
	v_max_f32_e32 v196, v196, v196
	v_max_f32_e32 v196, v196, v197
	s_waitcnt lgkmcnt(0)
	v_mfma_f32_32x32x16_bf16 v[48:63], v[160:163], v[216:219], v[48:63]
	ds_read_b64_tr_b16 v[216:217], v187 offset:0x400
	ds_read_b64_tr_b16 v[218:219], v187 offset:0xc00
	v_sub_f32_e32 v197, v196, v211
	v_cmp_ge_f32_e32 vcc, s85, v197
	v_max_f32_e32 v197, v211, v211
	v_max_f32_e32 v197, v197, v196
	v_sub_f32_e32 v196, v211, v197
	v_mul_f32_e32 v196, 0x3e0293ee, v196
	v_mfma_f32_32x32x16_bf16 v[48:63], v[164:167], v[220:223], v[48:63]
	ds_read_b64_tr_b16 v[220:221], v187 offset:0x1400
	ds_read_b64_tr_b16 v[222:223], v187 offset:0x1c00
	v_exp_f32_e32 v196, v196
	s_cmp_eq_u64 vcc, exec
	s_cselect_b64 s[42:43], -1, 0
	v_mfma_f32_32x32x16_bf16 v[48:63], v[168:171], v[224:227], v[48:63]
	ds_read_b64_tr_b16 v[224:225], v187 offset:0x2400
	ds_read_b64_tr_b16 v[226:227], v187 offset:0x2c00
	v_cndmask_b32_e64 v197, v197, v211, s[42:43]
	v_mul_f32_e32 v198, 0xbe0293ee, v197
	v_fmamk_f32 v80, v80, 0x3e0293ee, v198
	v_fmamk_f32 v81, v81, 0x3e0293ee, v198
	v_fmamk_f32 v82, v82, 0x3e0293ee, v198
	v_fmamk_f32 v83, v83, 0x3e0293ee, v198
	v_mfma_f32_32x32x16_bf16 v[48:63], v[172:175], v[228:231], v[48:63]
	ds_read_b64_tr_b16 v[228:229], v187 offset:0x3400
	ds_read_b64_tr_b16 v[230:231], v187 offset:0x3c00
	v_fmamk_f32 v84, v84, 0x3e0293ee, v198
	v_fmamk_f32 v85, v85, 0x3e0293ee, v198
	v_fmamk_f32 v86, v86, 0x3e0293ee, v198
	v_fmamk_f32 v87, v87, 0x3e0293ee, v198
	v_exp_f32_e32 v238, v80
	v_exp_f32_e32 v239, v81
	s_waitcnt lgkmcnt(0)
	v_mfma_f32_32x32x16_bf16 v[32:47], v[160:163], v[216:219], v[32:47]
	ds_read_b64_tr_b16 v[216:217], v187 offset:0x600
	ds_read_b64_tr_b16 v[218:219], v187 offset:0xe00
	v_fmamk_f32 v88, v88, 0x3e0293ee, v198
	v_fmamk_f32 v89, v89, 0x3e0293ee, v198
	v_fmamk_f32 v90, v90, 0x3e0293ee, v198
	v_fmamk_f32 v91, v91, 0x3e0293ee, v198
	v_exp_f32_e32 v240, v82
	v_exp_f32_e32 v246, v83
	v_mfma_f32_32x32x16_bf16 v[32:47], v[164:167], v[220:223], v[32:47]
	ds_read_b64_tr_b16 v[220:221], v187 offset:0x1600
	ds_read_b64_tr_b16 v[222:223], v187 offset:0x1e00
	v_fmamk_f32 v92, v92, 0x3e0293ee, v198
	v_fmamk_f32 v93, v93, 0x3e0293ee, v198
	v_fmamk_f32 v94, v94, 0x3e0293ee, v198
	v_fmamk_f32 v95, v95, 0x3e0293ee, v198
	v_exp_f32_e32 v247, v84
	v_exp_f32_e32 v248, v85
	v_mfma_f32_32x32x16_bf16 v[32:47], v[168:171], v[224:227], v[32:47]
	ds_read_b64_tr_b16 v[224:225], v187 offset:0x2600
	ds_read_b64_tr_b16 v[226:227], v187 offset:0x2e00
	v_exp_f32_e32 v249, v86
	v_exp_f32_e32 v250, v87
	v_exp_f32_e32 v251, v88
	v_mfma_f32_32x32x16_bf16 v[32:47], v[172:175], v[228:231], v[32:47]
	ds_read_b64_tr_b16 v[228:229], v187 offset:0x3600
	ds_read_b64_tr_b16 v[230:231], v187 offset:0x3e00
	v_exp_f32_e32 v252, v89
	v_exp_f32_e32 v253, v90
	v_exp_f32_e32 v241, v91
	s_waitcnt lgkmcnt(0)
	v_mfma_f32_32x32x16_bf16 v[16:31], v[160:163], v[216:219], v[16:31]
	v_exp_f32_e32 v243, v92
	v_exp_f32_e32 v244, v93
	v_mfma_f32_32x32x16_bf16 v[16:31], v[164:167], v[220:223], v[16:31]
	v_exp_f32_e32 v245, v94
	v_exp_f32_e32 v193, v95
	v_mfma_f32_32x32x16_bf16 v[16:31], v[168:171], v[224:227], v[16:31]
	v_mfma_f32_32x32x16_bf16 v[16:31], v[172:175], v[228:231], v[16:31]
	v_cndmask_b32_e64 v160, v196, 1.0, s[42:43]
	v_cmp_gt_f32_e32 vcc, 1.0, v160
	v_mov_b32_e32 v164, v197
	s_mov_b32 s98, s90
	s_mov_b32 s90, s92
	s_mov_b32 s92, s98
	s_mov_b32 s98, s91
	s_mov_b32 s91, s99
	s_mov_b32 s99, s98
	s_cbranch_vccz .LBB0_736
	s_and_saveexec_b64 s[2:3], s[40:41]
	ds_write_b32 v185, v160 offset:128
	s_or_b64 exec, exec, s[2:3]
	s_waitcnt lgkmcnt(0)
	v_add_u32_e32 v156, v177, v194
	ds_read_b128 v[144:147], v156 offset:224
	ds_read_b128 v[148:151], v156 offset:192
	ds_read_b128 v[152:155], v156 offset:160
	ds_read_b128 v[156:159], v156 offset:128
	s_waitcnt lgkmcnt(3)
	v_pk_mul_f32 v[12:13], v[12:13], v[144:145]
	s_waitcnt lgkmcnt(2)
	v_pk_mul_f32 v[8:9], v[8:9], v[148:149]
	s_waitcnt lgkmcnt(1)
	v_pk_mul_f32 v[4:5], v[4:5], v[152:153]
	v_pk_mul_f32 v[14:15], v[14:15], v[146:147]
	v_pk_mul_f32 v[10:11], v[10:11], v[150:151]
	v_pk_mul_f32 v[6:7], v[6:7], v[154:155]
	s_waitcnt lgkmcnt(0)
	v_pk_mul_f32 v[2:3], v[2:3], v[158:159]
	v_pk_mul_f32 v[0:1], v[0:1], v[156:157]
	v_pk_mul_f32 v[60:61], v[60:61], v[144:145]
	v_pk_mul_f32 v[56:57], v[56:57], v[148:149]
	v_pk_mul_f32 v[52:53], v[52:53], v[152:153]
	v_pk_mul_f32 v[62:63], v[62:63], v[146:147]
	v_pk_mul_f32 v[58:59], v[58:59], v[150:151]
	v_pk_mul_f32 v[54:55], v[54:55], v[154:155]
	v_pk_mul_f32 v[50:51], v[50:51], v[158:159]
	v_pk_mul_f32 v[48:49], v[48:49], v[156:157]
	v_pk_mul_f32 v[44:45], v[44:45], v[144:145]
	v_pk_mul_f32 v[40:41], v[40:41], v[148:149]
	v_pk_mul_f32 v[36:37], v[36:37], v[152:153]
	v_pk_mul_f32 v[46:47], v[46:47], v[146:147]
	v_pk_mul_f32 v[42:43], v[42:43], v[150:151]
	v_pk_mul_f32 v[38:39], v[38:39], v[154:155]
	v_pk_mul_f32 v[34:35], v[34:35], v[158:159]
	v_pk_mul_f32 v[32:33], v[32:33], v[156:157]
	v_pk_mul_f32 v[28:29], v[28:29], v[144:145]
	v_pk_mul_f32 v[24:25], v[24:25], v[148:149]
	v_pk_mul_f32 v[20:21], v[20:21], v[152:153]
	v_pk_mul_f32 v[30:31], v[30:31], v[146:147]
	v_pk_mul_f32 v[26:27], v[26:27], v[150:151]
	v_pk_mul_f32 v[22:23], v[22:23], v[154:155]
	v_pk_mul_f32 v[18:19], v[18:19], v[158:159]
	v_pk_mul_f32 v[16:17], v[16:17], v[156:157]

.Lattn_b_loop:


	v_exp_f32_e32 v156, v156
	v_exp_f32_e32 v157, v157
	v_add_f32_e32 v209, v238, v239
	s_waitcnt lgkmcnt(3)
	v_mfma_f32_32x32x16_bf16 v[80:95], v[214:217], v[124:127], 0
	v_exp_f32_e32 v154, v154
	v_exp_f32_e32 v155, v155
	v_add_f32_e32 v209, v240, v209
	v_add_f32_e32 v209, v246, v209
	s_waitcnt lgkmcnt(2)
	v_mfma_f32_32x32x16_bf16 v[64:79], v[218:221], v[124:127], 0
	ds_read_b128 v[214:217], v204 offset:49152
	ds_read_b128 v[218:221], v204 offset:57344
	v_exp_f32_e32 v148, v148
	v_exp_f32_e32 v149, v149
	v_add_f32_e32 v209, v247, v209
	v_add_f32_e32 v209, v248, v209
	s_waitcnt lgkmcnt(3)
	v_mfma_f32_32x32x16_bf16 v[80:95], v[222:225], v[120:123], v[80:95]
	v_exp_f32_e32 v146, v146
	v_exp_f32_e32 v147, v147
	v_add_f32_e32 v209, v249, v209
	v_add_f32_e32 v209, v250, v209
	s_waitcnt lgkmcnt(2)
	v_mfma_f32_32x32x16_bf16 v[64:79], v[226:229], v[120:123], v[64:79]
	ds_read_b128 v[222:225], v202 offset:49152
	ds_read_b128 v[226:229], v202 offset:57344
	v_exp_f32_e32 v144, v144
	v_exp_f32_e32 v145, v145
	v_add_f32_e32 v209, v251, v209
	v_add_f32_e32 v209, v252, v209
	s_waitcnt lgkmcnt(3)
	v_mfma_f32_32x32x16_bf16 v[80:95], v[214:217], v[116:119], v[80:95]
	v_exp_f32_e32 v158, v158
	v_exp_f32_e32 v159, v159
	v_add_f32_e32 v209, v253, v209
	v_add_f32_e32 v209, v241, v209
	s_waitcnt lgkmcnt(2)
	v_mfma_f32_32x32x16_bf16 v[64:79], v[218:221], v[116:119], v[64:79]
	ds_read_b128 v[214:217], v191 offset:49152
	ds_read_b128 v[218:221], v191 offset:57344
	v_exp_f32_e32 v152, v152
	v_exp_f32_e32 v153, v153
	v_add_f32_e32 v209, v243, v209
	v_add_f32_e32 v209, v244, v209
	s_waitcnt lgkmcnt(3)
	v_mfma_f32_32x32x16_bf16 v[80:95], v[222:225], v[112:115], v[80:95]
	v_exp_f32_e32 v150, v150
	v_exp_f32_e32 v151, v151
	v_add_f32_e32 v209, v245, v209
	v_add_f32_e32 v209, v193, v209
	s_waitcnt lgkmcnt(2)
	v_mfma_f32_32x32x16_bf16 v[64:79], v[226:229], v[112:115], v[64:79]
	ds_read_b128 v[222:225], v203 offset:49152
	ds_read_b128 v[226:229], v203 offset:57344
	v_add_f32_e32 v209, v156, v209
	v_add_f32_e32 v209, v157, v209
	v_add_f32_e32 v209, v154, v209
	v_add_f32_e32 v209, v155, v209
	v_cvt_pk_bf16_f32 v160, v238, v239
	v_cvt_pk_bf16_f32 v162, v247, v248
	s_waitcnt lgkmcnt(3)
	v_mfma_f32_32x32x16_bf16 v[80:95], v[214:217], v[108:111], v[80:95]
	v_add_f32_e32 v209, v148, v209
	v_add_f32_e32 v209, v149, v209
	v_add_f32_e32 v209, v146, v209
	v_add_f32_e32 v209, v147, v209
	v_cvt_pk_bf16_f32 v161, v240, v246
	v_cvt_pk_bf16_f32 v163, v249, v250
	s_waitcnt lgkmcnt(2)
	v_mfma_f32_32x32x16_bf16 v[64:79], v[218:221], v[108:111], v[64:79]
	ds_read_b128 v[214:217], v206 offset:49152
	ds_read_b128 v[218:221], v206 offset:57344
	v_add_f32_e32 v209, v144, v209
	v_add_f32_e32 v209, v145, v209
	v_add_f32_e32 v209, v158, v209
	v_add_f32_e32 v209, v159, v209
	v_permlane32_swap_b32_e32 v160, v162
	v_permlane32_swap_b32_e32 v161, v163
	s_waitcnt lgkmcnt(3)
	v_mfma_f32_32x32x16_bf16 v[80:95], v[222:225], v[104:107], v[80:95]
	v_add_f32_e32 v209, v152, v209
	v_add_f32_e32 v209, v153, v209
	v_add_f32_e32 v209, v150, v209
	v_add_f32_e32 v209, v151, v209
	v_cvt_pk_bf16_f32 v170, v251, v252
	v_cvt_pk_bf16_f32 v172, v243, v244
	s_waitcnt lgkmcnt(2)
	v_mfma_f32_32x32x16_bf16 v[64:79], v[226:229], v[104:107], v[64:79]
	ds_read_b128 v[222:225], v207 offset:49152
	ds_read_b128 v[226:229], v207 offset:57344
	s_waitcnt vmcnt(0)
	v_add_u32_e32 v196, s92, v183
	v_add_u32_e32 v198, s92, v184
	ds_write_b128 v188, v[136:139] offset:32768
	ds_write_b128 v189, v[140:143] offset:32768
	ds_write_b128 v196, v[128:131]
	ds_write_b128 v198, v[132:135]
	v_mov_b32_e32 v210, v209
	v_cvt_pk_bf16_f32 v171, v253, v241
	v_cvt_pk_bf16_f32 v173, v245, v193
	v_cvt_pk_bf16_f32 v166, v156, v157
	v_cvt_pk_bf16_f32 v168, v148, v149
	s_waitcnt lgkmcnt(7)
	v_mfma_f32_32x32x16_bf16 v[80:95], v[214:217], v[100:103], v[80:95]
	v_permlane32_swap_b32_e32 v209, v210
	v_permlane32_swap_b32_e32 v170, v172
	v_permlane32_swap_b32_e32 v171, v173
	v_cvt_pk_bf16_f32 v167, v154, v155
	v_cvt_pk_bf16_f32 v169, v146, v147
	s_waitcnt lgkmcnt(6)
	v_mfma_f32_32x32x16_bf16 v[64:79], v[218:221], v[100:103], v[64:79]
	v_permlane32_swap_b32_e32 v166, v168
	v_cvt_pk_bf16_f32 v212, v144, v145
	v_cvt_pk_bf16_f32 v213, v158, v159
	s_waitcnt lgkmcnt(5)
	v_mfma_f32_32x32x16_bf16 v[80:95], v[222:225], v[96:99], v[80:95]
	v_permlane32_swap_b32_e32 v167, v169
	v_cvt_pk_bf16_f32 v214, v152, v153
	v_cvt_pk_bf16_f32 v215, v150, v151
	s_waitcnt lgkmcnt(4)
	v_mfma_f32_32x32x16_bf16 v[64:79], v[226:229], v[96:99], v[64:79]
	v_permlane32_swap_b32_e32 v212, v214
	v_permlane32_swap_b32_e32 v213, v215
	v_add_u32_e32 v187, s90, v182
	ds_read_b64_tr_b16 v[216:217], v187 offset:0
	ds_read_b64_tr_b16 v[218:219], v187 offset:0x800
	ds_read_b64_tr_b16 v[220:221], v187 offset:0x1000
	ds_read_b64_tr_b16 v[222:223], v187 offset:0x1800
	ds_read_b64_tr_b16 v[224:225], v187 offset:0x2000
	ds_read_b64_tr_b16 v[226:227], v187 offset:0x2800
	ds_read_b64_tr_b16 v[228:229], v187 offset:0x3000
	ds_read_b64_tr_b16 v[230:231], v187 offset:0x3800
	s_mov_b32 s2, 0xfffb8000
	v_add_co_u32_e32 v148, vcc, s2, v178
	s_mov_b32 s2, 0xfffd0000
	s_nop 0
	v_addc_co_u32_e32 v149, vcc, -1, v179, vcc
	v_add_co_u32_e32 v152, vcc, s2, v178
	s_nop 1
	v_addc_co_u32_e32 v153, vcc, -1, v179, vcc
	global_load_dwordx4 v[144:147], v[148:149], off
	s_nop 0
	global_load_dwordx4 v[148:151], v[148:149], off offset:-512
	s_nop 0
	global_load_dwordx4 v[156:159], v[152:153], off
	s_nop 0
	global_load_dwordx4 v[152:155], v[152:153], off offset:-512
	v_max_f32_e32 v196, v81, v81
	v_max_f32_e32 v197, v80, v80
	v_max_f32_e32 v196, v197, v196
	v_max3_f32 v196, v196, v82, v83
	v_max3_f32 v196, v196, v84, v85
	v_max3_f32 v196, v196, v86, v87
	v_max3_f32 v196, v196, v88, v89
	s_waitcnt lgkmcnt(0)
	s_barrier
	v_mfma_f32_32x32x16_bf16 v[0:15], v[160:163], v[216:219], v[0:15]
	ds_read_b64_tr_b16 v[216:217], v187 offset:0x200
	ds_read_b64_tr_b16 v[218:219], v187 offset:0xa00
	v_max3_f32 v196, v196, v90, v91
	v_max3_f32 v196, v196, v92, v93
	v_max3_f32 v196, v196, v94, v95
	v_max3_f32 v196, v196, v64, v65
	v_mfma_f32_32x32x16_bf16 v[0:15], v[170:173], v[220:223], v[0:15]
	ds_read_b64_tr_b16 v[220:221], v187 offset:0x1200
	ds_read_b64_tr_b16 v[222:223], v187 offset:0x1a00
	v_max3_f32 v196, v196, v66, v67
	v_max3_f32 v196, v196, v68, v69
	v_max3_f32 v196, v196, v70, v71
	v_max3_f32 v196, v196, v72, v73
	v_mfma_f32_32x32x16_bf16 v[0:15], v[166:169], v[224:227], v[0:15]
	ds_read_b64_tr_b16 v[224:225], v187 offset:0x2200
	ds_read_b64_tr_b16 v[226:227], v187 offset:0x2a00
	v_max3_f32 v196, v196, v74, v75
	v_max3_f32 v196, v196, v76, v77
	v_max3_f32 v196, v196, v78, v79
	v_mov_b32_e32 v197, v196
	v_mfma_f32_32x32x16_bf16 v[0:15], v[212:215], v[228:231], v[0:15]
	ds_read_b64_tr_b16 v[228:229], v187 offset:0x3200
	ds_read_b64_tr_b16 v[230:231], v187 offset:0x3a00
	v_permlane32_swap_b32_e32 v196, v197
	v_max_f32_e32 v197, v197, v197
	v_max_f32_e32 v196, v196, v196
	v_max_f32_e32 v196, v196, v197
	s_waitcnt lgkmcnt(0)
	v_mfma_f32_32x32x16_bf16 v[48:63], v[160:163], v[216:219], v[48:63]
	ds_read_b64_tr_b16 v[216:217], v187 offset:0x400
	ds_read_b64_tr_b16 v[218:219], v187 offset:0xc00
	v_sub_f32_e32 v197, v196, v164
	v_cmp_ge_f32_e32 vcc, s85, v197
	v_max_f32_e32 v197, v164, v164
	v_max_f32_e32 v196, v197, v196
	v_sub_f32_e32 v197, v164, v196
	v_mul_f32_e32 v197, 0x3e0293ee, v197
	v_mfma_f32_32x32x16_bf16 v[48:63], v[170:173], v[220:223], v[48:63]
	ds_read_b64_tr_b16 v[220:221], v187 offset:0x1400
	ds_read_b64_tr_b16 v[222:223], v187 offset:0x1c00
	v_exp_f32_e32 v197, v197
	s_cmp_eq_u64 vcc, exec
	s_cselect_b64 s[42:43], -1, 0
	v_mfma_f32_32x32x16_bf16 v[48:63], v[166:169], v[224:227], v[48:63]
	ds_read_b64_tr_b16 v[224:225], v187 offset:0x2400
	ds_read_b64_tr_b16 v[226:227], v187 offset:0x2c00
	v_cndmask_b32_e64 v211, v196, v164, s[42:43]
	v_mul_f32_e32 v198, 0xbe0293ee, v211
	v_fmamk_f32 v80, v80, 0x3e0293ee, v198
	v_fmamk_f32 v81, v81, 0x3e0293ee, v198
	v_fmamk_f32 v82, v82, 0x3e0293ee, v198
	v_fmamk_f32 v83, v83, 0x3e0293ee, v198
	v_mfma_f32_32x32x16_bf16 v[48:63], v[212:215], v[228:231], v[48:63]
	ds_read_b64_tr_b16 v[228:229], v187 offset:0x3400
	ds_read_b64_tr_b16 v[230:231], v187 offset:0x3c00
	v_fmamk_f32 v84, v84, 0x3e0293ee, v198
	v_fmamk_f32 v85, v85, 0x3e0293ee, v198
	v_fmamk_f32 v86, v86, 0x3e0293ee, v198
	v_fmamk_f32 v87, v87, 0x3e0293ee, v198
	v_exp_f32_e32 v238, v80
	v_exp_f32_e32 v239, v81
	s_waitcnt lgkmcnt(0)
	v_mfma_f32_32x32x16_bf16 v[32:47], v[160:163], v[216:219], v[32:47]
	ds_read_b64_tr_b16 v[216:217], v187 offset:0x600
	ds_read_b64_tr_b16 v[218:219], v187 offset:0xe00
	v_fmamk_f32 v88, v88, 0x3e0293ee, v198
	v_fmamk_f32 v89, v89, 0x3e0293ee, v198
	v_fmamk_f32 v90, v90, 0x3e0293ee, v198
	v_fmamk_f32 v91, v91, 0x3e0293ee, v198
	v_exp_f32_e32 v240, v82
	v_exp_f32_e32 v246, v83
	v_mfma_f32_32x32x16_bf16 v[32:47], v[170:173], v[220:223], v[32:47]
	ds_read_b64_tr_b16 v[220:221], v187 offset:0x1600
	ds_read_b64_tr_b16 v[222:223], v187 offset:0x1e00
	v_fmamk_f32 v92, v92, 0x3e0293ee, v198
	v_fmamk_f32 v93, v93, 0x3e0293ee, v198
	v_fmamk_f32 v94, v94, 0x3e0293ee, v198
	v_fmamk_f32 v95, v95, 0x3e0293ee, v198
	v_exp_f32_e32 v247, v84
	v_exp_f32_e32 v248, v85
	v_mfma_f32_32x32x16_bf16 v[32:47], v[166:169], v[224:227], v[32:47]
	ds_read_b64_tr_b16 v[224:225], v187 offset:0x2600
	ds_read_b64_tr_b16 v[226:227], v187 offset:0x2e00
	v_exp_f32_e32 v249, v86
	v_exp_f32_e32 v250, v87
	v_exp_f32_e32 v251, v88
	v_mfma_f32_32x32x16_bf16 v[32:47], v[212:215], v[228:231], v[32:47]
	ds_read_b64_tr_b16 v[228:229], v187 offset:0x3600
	ds_read_b64_tr_b16 v[230:231], v187 offset:0x3e00
	v_exp_f32_e32 v252, v89
	v_exp_f32_e32 v253, v90
	v_exp_f32_e32 v241, v91
	s_waitcnt lgkmcnt(0)
	v_mfma_f32_32x32x16_bf16 v[16:31], v[160:163], v[216:219], v[16:31]
	v_exp_f32_e32 v243, v92
	v_exp_f32_e32 v244, v93
	v_mfma_f32_32x32x16_bf16 v[16:31], v[170:173], v[220:223], v[16:31]
	v_exp_f32_e32 v245, v94
	v_exp_f32_e32 v193, v95
	v_mfma_f32_32x32x16_bf16 v[16:31], v[166:169], v[224:227], v[16:31]
	v_mfma_f32_32x32x16_bf16 v[16:31], v[212:215], v[228:231], v[16:31]
	v_cndmask_b32_e64 v213, v197, 1.0, s[42:43]
	v_cmp_gt_f32_e32 vcc, 1.0, v213
	v_mul_f32_e32 v212, 0xbe0293ee, v211
	s_add_i32 s11, s11, 2
	s_nop 3
	s_cbranch_vccz .Lattn_b_skip_ra
	s_and_saveexec_b64 s[2:3], s[40:41]
	ds_write_b32 v185, v213 offset:128
	s_or_b64 exec, exec, s[2:3]
	s_waitcnt lgkmcnt(0)
	v_add_u32_e32 v161, v177, v194
	ds_read_b128 v[166:169], v161 offset:224
	ds_read_b128 v[170:173], v161 offset:192
	ds_read_b128 v[214:217], v161 offset:160
	ds_read_b128 v[218:221], v161 offset:128
	s_waitcnt lgkmcnt(3)
	v_pk_mul_f32 v[12:13], v[12:13], v[166:167]
	s_waitcnt lgkmcnt(2)
	v_pk_mul_f32 v[8:9], v[8:9], v[170:171]
	s_waitcnt lgkmcnt(1)
	v_pk_mul_f32 v[4:5], v[4:5], v[214:215]
	v_pk_mul_f32 v[14:15], v[14:15], v[168:169]
	v_pk_mul_f32 v[10:11], v[10:11], v[172:173]
	v_pk_mul_f32 v[6:7], v[6:7], v[216:217]
	s_waitcnt lgkmcnt(0)
	v_pk_mul_f32 v[2:3], v[2:3], v[220:221]
	v_pk_mul_f32 v[0:1], v[0:1], v[218:219]
	v_pk_mul_f32 v[60:61], v[60:61], v[166:167]
	v_pk_mul_f32 v[56:57], v[56:57], v[170:171]
	v_pk_mul_f32 v[52:53], v[52:53], v[214:215]
	v_pk_mul_f32 v[62:63], v[62:63], v[168:169]
	v_pk_mul_f32 v[58:59], v[58:59], v[172:173]
	v_pk_mul_f32 v[54:55], v[54:55], v[216:217]
	v_pk_mul_f32 v[50:51], v[50:51], v[220:221]
	v_pk_mul_f32 v[48:49], v[48:49], v[218:219]
	v_pk_mul_f32 v[44:45], v[44:45], v[166:167]
	v_pk_mul_f32 v[40:41], v[40:41], v[170:171]
	v_pk_mul_f32 v[36:37], v[36:37], v[214:215]
	v_pk_mul_f32 v[46:47], v[46:47], v[168:169]
	v_pk_mul_f32 v[42:43], v[42:43], v[172:173]
	v_pk_mul_f32 v[38:39], v[38:39], v[216:217]
	v_pk_mul_f32 v[34:35], v[34:35], v[220:221]
	v_pk_mul_f32 v[32:33], v[32:33], v[218:219]
	v_pk_mul_f32 v[28:29], v[28:29], v[166:167]
	v_pk_mul_f32 v[24:25], v[24:25], v[170:171]
	v_pk_mul_f32 v[20:21], v[20:21], v[214:215]
	v_pk_mul_f32 v[30:31], v[30:31], v[168:169]
	v_pk_mul_f32 v[26:27], v[26:27], v[172:173]
	v_pk_mul_f32 v[22:23], v[22:23], v[216:217]
	v_pk_mul_f32 v[18:19], v[18:19], v[220:221]
	v_pk_mul_f32 v[16:17], v[16:17], v[218:219]
